# also staggers half the WGs by 6us at GEMM1 start
# baseline (speedup 1.0000x reference)
; #define WSB_DECL unsigned char* wsb = A.ws; asm volatile("" : "+s"(wsb))
; __global__ void __launch_bounds__(NWAVES * 64, 2) hybrid_fwd(Args A) {
;     ...
;     for (int ph = lo; ph < hi; ++ph) {
;       const int l = (ph - 1) / 6, s = (ph == 0) ? -1 : (ph - 1) % 6;
;       WSB_DECL;
;       const int reps = ((ph > 0 && ((DUP_MASK >> s) & 1) && !(s == 5 && l == DEPTH - 1)) || (ph == 0 && (DUP_MASK & 64))) ? 2 : 1;
;       for (int rep = 0; rep < reps; ++rep) {
;         if (rep) { if (ph == 0) cg::this_grid().sync(); else xcd_barrier(bar); }
;         if (ph == 0) { if (EN(0)) phase_prologue(A, C); }
;         else {
;             if (s == 0 && EN(1)) { pg8::Gemm g{WS_PTR(const bf16, WS_HB), WS_PTR(const bf16, WS_WINT) + (size_t)l * DINP * D, M, DINP, D, D}; pg8::StaticOrder S; S.init(M, DINP, C.G, C.bid);
.LBB0_19:
	s_mov_b64 s[0:1], s[24:25]
	v_writelane_b32 v255, s0, 36
	s_nop 1
	v_writelane_b32 v255, s1, 37
	v_writelane_b32 v255, s2, 38
	v_writelane_b32 v255, s3, 39
	v_sub_co_u32_e64 v0, s[0:1], s24, 1
	s_nop 0
	v_readfirstlane_b32 s2, v0
	s_mul_hi_i32 s3, s2, 0x2aaaaaab
	s_lshr_b32 s8, s3, 31
	s_add_i32 s8, s3, s8
	s_mul_i32 s3, s8, 6
	s_sub_i32 s10, s2, s3
	s_cmp_eq_u32 s10, 5
	s_cselect_b64 s[2:3], -1, 0
	v_writelane_b32 v255, s2, 40
	s_andn2_b64 vcc, exec, s[0:1]
	s_mov_b64 s[0:1], -1
	v_writelane_b32 v255, s3, 41
	s_cmp_eq_u32 s10, 0
	s_cbranch_scc0 .Lmy_nostag0
	v_readlane_b32 s2, v253, 0
	s_nop 0
	s_bitcmp1_b32 s2, 3
	s_cbranch_scc0 .Lmy_nostag0
	s_memrealtime s[98:99]
	s_waitcnt lgkmcnt(0)
	s_add_u32 s2, s98, 600

; __global__ void __launch_bounds__(NWAVES * 64, 2) hybrid_fwd(Args A) {
;     ...
;             else if ((s == 2 && EN(3)) || (s == 3 && EN(4)) || (s == 4 && EN(5))) {
;                 const bool split = C.G >= 192; bool go = (s == 4); int k0 = split ? KSPLIT : 0, kl = D - k0, gg = C.G, cc = C.bid, mrows = M; size_t roff = 0;
;                 if (s == 2) { go = phase_mixers(A, C, l, rep ? DUP_UN : 7); k0 = 0; kl = KSPLIT; gg = C.G - 128; cc = C.bid - 128; mrows = MP; }
.Lmy_nostag0:
	s_cmp_eq_u32 s10, 4
	s_cbranch_scc0 .Lmy_nostag4
	v_readlane_b32 s2, v253, 0
	s_nop 0
	s_bitcmp1_b32 s2, 3
	s_cbranch_scc0 .Lmy_nostag4
	s_memrealtime s[98:99]
	s_waitcnt lgkmcnt(0)
	s_add_u32 s2, s98, 1600
